# same as previous plus thin-phase grid 176 (mixers 6+6+2 units on every thin workgroup, gate GEMM exactly 14 rounds)
# speedup vs baseline: 1.0114x; 1.0027x over previous
; #define LAS __attribute__((address_space(3)))
;     __device__ __forceinline__ const float* in(int i) const { return (const float*)(const __attribute__((address_space(1))) float*)get(i); }
;     __device__ __forceinline__ float* out() const { return (float*)(__attribute__((address_space(1))) float*)get(34); }
;     __device__ __forceinline__ unsigned char* ws() const { return (unsigned char*)(__attribute__((address_space(1))) unsigned char*)get(35); }
; #define RUN(REPS, GSEL, ...) _Pragma("unroll 1") for (int rep_ = 0; rep_ < (REPS); ++rep_) { { const int Gsel = (GSEL); if (bid0 < Gsel) { __VA_ARGS__ } } GRID_BAR(); }
; __global__ void __launch_bounds__(512, 2) mega_fwd(Args args) {
;     ...
;     const int Ggemm = (int)gridDim.x, Gthin = Ggemm < THIN_GRID ? Ggemm : THIN_GRID;
;     const int bid0 = blockIdx.x, G0 = gridDim.x, wave_s = __builtin_amdgcn_readfirstlane((int)threadIdx.x >> 6);
;     volatile LAS unsigned* MISC = (volatile LAS unsigned*)(ldsL + MISC_OFF);
;     PA a; a.tab = MISC + 64;
;     ...
;     if (threadIdx.x < 64) MISC[threadIdx.x] = 0u;
;     ...
;     if (threadIdx.x == 64) {
; #pragma unroll
;         for (int i = 0; i < 34; ++i) { const unsigned long long v = (unsigned long long)args.in[i]; a.tab[2 * i] = (unsigned)v; a.tab[2 * i + 1] = (unsigned)(v >> 32); }
;         { const unsigned long long v = (unsigned long long)args.out; a.tab[68] = (unsigned)v; a.tab[69] = (unsigned)(v >> 32); }
;         { const unsigned long long v = (unsigned long long)args.ws; a.tab[70] = (unsigned)v; a.tab[71] = (unsigned)(v >> 32); }
;     }
;     __syncthreads();
;     ...
;     { XcdBarrier bar0 = xcd_barrier_post((unsigned*)(a.ws() + WS_CTL) + CW_BAR, MISC + 8); (void)bar0; }
;     ...
;     RUN(1, Ggemm, { PH_BEGIN prologue_block(a, bid, ldsL, tid); if (bid >= 193 && bid < 193 + 32) s5disc_thread(a, (bid - 193) * 512 + tid); __syncthreads(); }
;         { PH_BEGIN convert_layer(a, 0, (LAS float*)ldsL + wave * 32 * 65, gw, NGW, lane, bid * 512 + tid, G * 512); } )
;     for (int l = 0; l < DEPTH; ++l) {
;         const int Mrows = (l == DEPTH - 1) ? NLAT : NTOK;
;         const int cb_ = (Ggemm - GRID_C >= 32) ? GRID_C : 0;
;         const int eC = ECR * (Ggemm - GRID_C), eC2 = eC, eD = eC2 + 1 * (Ggemm - GRID_D);
.LBB0_160:
	s_or_b64 exec, exec, s[0:1]
	s_min_i32 s92, s87, 0xb0
	s_sub_i32 s0, s87, s92
	s_cmp_gt_i32 s0, 31
	s_cselect_b32 s1, s92, 0
	s_mul_i32 s75, s0, 8
	s_cmp_lt_i32 s81, s92
	s_cselect_b64 s[2:3], -1, 0
	s_cmp_ge_i32 s81, s92
	v_writelane_b32 v254, s2, 0
	s_cselect_b64 s[94:95], -1, 0
	s_cmp_eq_u32 s1, 0
	v_writelane_b32 v254, s3, 1
	s_cselect_b64 s[2:3], -1, 0
	v_writelane_b32 v254, s2, 2
	s_cmp_lg_u32 s1, 0
	s_mul_i32 s90, s0, 7
	v_writelane_b32 v254, s3, 3
	v_writelane_b32 v254, s1, 4
	s_cselect_b64 s[0:1], -1, 0
	v_writelane_b32 v254, s0, 5
	s_add_i32 s61, 0, 0x10400
	s_add_i32 s76, 0, 0x14400
	v_writelane_b32 v254, s1, 6
	s_add_i32 s0, 0, 0x18400
	v_writelane_b32 v254, s0, 7
	s_add_i32 s0, 0, 0x20020
	v_writelane_b32 v254, s0, 8
	s_add_i32 s0, 0, 0x20024
	v_writelane_b32 v254, s0, 9
	s_add_i32 s0, 0, 0x10200
	v_writelane_b32 v254, s0, 10
	s_mov_b64 s[0:1], 0
	v_writelane_b32 v254, s0, 11
	s_mov_b32 s80, 0x8000
	v_mov_b32_e32 v250, 0x358637bd
	v_writelane_b32 v254, s1, 12
	s_mov_b64 s[0:1], 0x40000
	v_writelane_b32 v254, s0, 13
	s_mov_b32 s97, 0xf800000
	v_mov_b32_e32 v251, 0x260
	v_writelane_b32 v254, s1, 14
	s_mov_b64 s[0:1], 0
	v_writelane_b32 v254, s0, 15
	s_movk_i32 s64, 0x7fff
	s_movk_i32 s86, 0x3ff
	v_writelane_b32 v254, s1, 16
	v_writelane_b32 v254, s61, 17
	v_writelane_b32 v254, s76, 18
	v_writelane_b32 v254, s79, 19
	v_writelane_b32 v254, s87, 20
	v_writelane_b32 v254, s81, 21
	v_writelane_b32 v254, s82, 22
	s_movk_i32 s66, 0x1000
	s_mov_b32 s67, 0x56801000
	v_writelane_b32 v254, s83, 23
	v_writelane_b32 v254, s84, 24
	s_mov_b32 s68, 0x57001000
	s_mov_b32 s69, 0x57801000
	v_writelane_b32 v254, s85, 25
	v_writelane_b32 v254, s93, 26
	v_writelane_b32 v254, s88, 27
	s_mov_b32 s70, 0x58001000
	s_movk_i32 s60, 0x4000
	v_writelane_b32 v254, s89, 28
	v_writelane_b32 v254, s92, 29
	v_writelane_b32 v254, s90, 30
	v_writelane_b32 v254, s75, 31
	v_writelane_b32 v254, s94, 32
	s_add_i32 s33, 0, 0x14000
	s_movk_i32 s65, 0x67f
	v_mov_b32_e32 v252, 1.0
	s_movk_i32 s30, 0x41
	s_movk_i32 s77, 0x7dff
	s_mov_b32 s78, 0x200000
	s_mov_b32 s74, 0x240000
	s_mov_b32 s71, 0x280000
	s_mov_b32 s72, 0x2c0000
	v_mov_b32_e32 v253, 0xf149f2ca
	v_mov_b32_e32 v209, 0
	s_mov_b32 s96, 0
	s_mov_b32 s59, 0
	s_mov_b64 s[2:3], 0x80
	s_mov_b64 s[42:43], 0x14a00400
	v_writelane_b32 v254, s95, 33
	s_waitcnt lgkmcnt(0)
	s_barrier
	s_branch .LBB0_163
